# baseline (speedup 1.0000x reference)
; __device__ __forceinline__ void phase_branch_norm(bf16_t* y, const float* ga, const float* gs, const float* gg, const Ctx cx) {
;     ...
;     for (int m = gw; m < T; m += NGW) {
;         bf16_t* yr = y + (size_t)m * DM + lane * 8;
;         float v[4][8]; float ss[4];
; #pragma unroll
;         for (int j = 0; j < 4; ++j) { const u32x4 w = *(const u32x4*)(yr + j * 512);
;             v[j][0] = bflo(w.x); v[j][1] = bfhi(w.x); v[j][2] = bflo(w.y); v[j][3] = bfhi(w.y); v[j][4] = bflo(w.z); v[j][5] = bfhi(w.z); v[j][6] = bflo(w.w); v[j][7] = bfhi(w.w);
;             float s = 0.f;
; #pragma unroll
;             for (int e = 0; e < 8; ++e) s += v[j][e] * v[j][e];
;             ss[j] = s; }
;         const float sa = wave_sum(ss[0] + ss[1]), s2 = wave_sum(ss[2]), s3 = wave_sum(ss[3]);
;         const float ra = 1.0f / sqrtf(sa * (1.0f / 1024.f) + EPS), rs = 1.0f / sqrtf(s2 * (1.0f / 512.f) + EPS), rg = 1.0f / sqrtf(s3 * (1.0f / 512.f) + EPS);
; #pragma unroll
.LBB0_467:
	global_load_dwordx4 v[46:49], v[38:39], off
	global_load_dwordx4 v[54:57], v[38:39], off offset:1024
	global_load_dwordx4 v[34:37], v[38:39], off offset:2048
	global_load_dwordx4 v[30:33], v[38:39], off offset:3072
	s_add_i32 s4, s4, s6
	s_cmp_lt_i32 s4, 0x8000
	s_waitcnt vmcnt(3)
	v_and_b32_e32 v44, 0xffff0000, v46
	s_waitcnt vmcnt(2)
	v_and_b32_e32 v52, 0xffff0000, v54
	v_lshlrev_b32_e32 v42, 16, v46
	v_lshlrev_b32_e32 v50, 16, v54
	v_mov_b32_e32 v68, v44
	v_mov_b32_e32 v69, v52
	v_lshlrev_b32_e32 v43, 16, v47
	v_lshlrev_b32_e32 v51, 16, v55
	v_mov_b32_e32 v60, v42
	v_mov_b32_e32 v61, v50
	v_pk_mul_f32 v[68:69], v[68:69], v[68:69]
	v_and_b32_e32 v45, 0xffff0000, v47
	v_and_b32_e32 v53, 0xffff0000, v55
	v_mov_b32_e32 v70, v43
	v_mov_b32_e32 v71, v51
	v_pk_fma_f32 v[60:61], v[60:61], v[60:61], v[68:69]
	v_lshlrev_b32_e32 v46, 16, v48
	v_lshlrev_b32_e32 v54, 16, v56
	v_mov_b32_e32 v72, v45
	v_mov_b32_e32 v73, v53
	v_pk_fma_f32 v[60:61], v[70:71], v[70:71], v[60:61]
	v_and_b32_e32 v48, 0xffff0000, v48
	v_and_b32_e32 v56, 0xffff0000, v56
	v_mov_b32_e32 v74, v46
	v_mov_b32_e32 v75, v54
	v_pk_fma_f32 v[60:61], v[72:73], v[72:73], v[60:61]
	v_lshlrev_b32_e32 v47, 16, v49
	v_lshlrev_b32_e32 v55, 16, v57
	v_mov_b32_e32 v76, v48
	v_mov_b32_e32 v77, v56
	v_pk_fma_f32 v[60:61], v[74:75], v[74:75], v[60:61]
	v_and_b32_e32 v49, 0xffff0000, v49
	v_and_b32_e32 v57, 0xffff0000, v57
	v_mov_b32_e32 v78, v47
	v_mov_b32_e32 v79, v55
	v_pk_fma_f32 v[60:61], v[76:77], v[76:77], v[60:61]
	v_mov_b32_e32 v80, v49
	v_mov_b32_e32 v81, v57
	v_pk_fma_f32 v[60:61], v[78:79], v[78:79], v[60:61]
	s_waitcnt vmcnt(1)
	v_lshlrev_b32_e32 v59, 16, v35
	v_pk_fma_f32 v[60:61], v[80:81], v[80:81], v[60:61]
	v_lshlrev_b32_e32 v58, 16, v34
	v_add_f32_e32 v68, v60, v61
	s_nop 1
	v_add_f32_dpp v118, v68, v68 quad_perm:[1,0,3,2] row_mask:0xf bank_mask:0xf
	s_nop 1
	v_add_f32_dpp v118, v118, v118 quad_perm:[2,3,0,1] row_mask:0xf bank_mask:0xf
	s_nop 1
	v_add_f32_dpp v118, v118, v118 row_half_mirror row_mask:0xf bank_mask:0xf
	s_nop 1
	v_add_f32_dpp v118, v118, v118 row_mirror row_mask:0xf bank_mask:0xf
	s_nop 1
	v_add_f32_dpp v118, v118, v118 row_bcast:15 row_mask:0xa bank_mask:0xf
	s_nop 1
	v_add_f32_dpp v118, v118, v118 row_bcast:31 row_mask:0xc bank_mask:0xf
	s_nop 1
	v_readlane_b32 s80, v118, 63
	v_and_b32_e32 v61, 0xffff0000, v35
	v_and_b32_e32 v60, 0xffff0000, v34
	v_lshlrev_b32_e32 v35, 16, v37
	v_lshlrev_b32_e32 v34, 16, v36
	v_pk_mul_f32 v[68:69], v[58:59], v[58:59]
	v_and_b32_e32 v37, 0xffff0000, v37
	v_and_b32_e32 v36, 0xffff0000, v36
	v_mov_b32_e32 v72, v37
	v_pk_mul_f32 v[70:71], v[60:61], v[60:61]
	v_mov_b32_e32 v73, v35
	v_add_f32_e32 v68, v68, v70
	v_add_f32_e32 v68, v69, v68
	v_add_f32_e32 v68, v71, v68
	v_fmac_f32_e32 v68, v34, v34
	v_pk_mul_f32 v[72:73], v[72:73], v[72:73]
	v_fmac_f32_e32 v68, v36, v36
	v_add_f32_e32 v68, v73, v68
	v_add_f32_e32 v68, v72, v68
	s_nop 1
	v_add_f32_dpp v119, v68, v68 quad_perm:[1,0,3,2] row_mask:0xf bank_mask:0xf
	s_nop 1
	v_add_f32_dpp v119, v119, v119 quad_perm:[2,3,0,1] row_mask:0xf bank_mask:0xf
	s_nop 1
	v_add_f32_dpp v119, v119, v119 row_half_mirror row_mask:0xf bank_mask:0xf
	s_nop 1
	v_add_f32_dpp v119, v119, v119 row_mirror row_mask:0xf bank_mask:0xf
	s_nop 1
	v_add_f32_dpp v119, v119, v119 row_bcast:15 row_mask:0xa bank_mask:0xf
	s_nop 1
	v_add_f32_dpp v119, v119, v119 row_bcast:31 row_mask:0xc bank_mask:0xf
	s_nop 1
	v_readlane_b32 s81, v119, 63
	s_nop 1
	v_mov_b32_e32 v69, s80
	v_fmamk_f32 v69, v69, 0x3a800000, v194
	v_mul_f32_e32 v70, 0x4f800000, v69
	v_cmp_gt_f32_e32 vcc, s13, v69
	v_cndmask_b32_e32 v69, v69, v70, vcc
	v_sqrt_f32_e32 v70, v69
	s_nop 0
	v_add_u32_e32 v68, -1, v70
	v_add_u32_e32 v72, 1, v70
	v_fma_f32 v73, -v68, v70, v69
	v_fma_f32 v74, -v72, v70, v69
	v_cmp_ge_f32_e64 s[0:1], 0, v73
	s_nop 1
	v_cndmask_b32_e64 v68, v70, v68, s[0:1]
	v_cmp_lt_f32_e64 s[0:1], 0, v74
	s_nop 1
	v_cndmask_b32_e64 v68, v68, v72, s[0:1]
	v_mul_f32_e32 v70, 0x37800000, v68
	v_cndmask_b32_e32 v68, v68, v70, vcc
	v_cmp_class_f32_e32 vcc, v69, v195
	s_nop 0
	v_cndmask_b32_e32 v68, v68, v69, vcc
	v_div_scale_f32 v69, s[0:1], v68, v68, 1.0
	v_rcp_f32_e32 v70, v69
	v_div_scale_f32 v73, vcc, 1.0, v68, 1.0
	v_fma_f32 v74, -v69, v70, 1.0
	v_fmac_f32_e32 v70, v74, v70
	v_mul_f32_e32 v74, v73, v70
	v_fma_f32 v75, -v69, v74, v73
	v_fmac_f32_e32 v74, v75, v70
	v_fma_f32 v69, -v69, v74, v73
	v_div_fmas_f32 v69, v69, v70, v74
	v_div_fixup_f32 v68, v69, v68, 1.0
	v_pk_mul_f32 v[42:43], v[68:69], v[42:43] op_sel_hi:[0,1]
	v_pk_mul_f32 v[46:47], v[68:69], v[46:47] op_sel_hi:[0,1]
	v_pk_mul_f32 v[48:49], v[68:69], v[48:49] op_sel_hi:[0,1]
	v_pk_mul_f32 v[44:45], v[68:69], v[44:45] op_sel_hi:[0,1]
	v_pk_mul_f32 v[50:51], v[68:69], v[50:51] op_sel_hi:[0,1]
	v_pk_mul_f32 v[52:53], v[68:69], v[52:53] op_sel_hi:[0,1]
	v_pk_mul_f32 v[54:55], v[68:69], v[54:55] op_sel_hi:[0,1]
	v_pk_mul_f32 v[56:57], v[68:69], v[56:57] op_sel_hi:[0,1]
	v_pk_mul_f32 v[68:69], v[16:17], v[42:43]
	v_pk_mul_f32 v[46:47], v[20:21], v[46:47]
	v_pk_mul_f32 v[48:49], v[18:19], v[48:49]
	v_pk_mul_f32 v[44:45], v[14:15], v[44:45]
	v_pk_mul_f32 v[42:43], v[24:25], v[50:51]
	v_pk_mul_f32 v[50:51], v[22:23], v[52:53]
	v_pk_mul_f32 v[52:53], v[28:29], v[54:55]
	v_pk_mul_f32 v[54:55], v[26:27], v[56:57]
	v_bfe_u32 v56, v49, 16, 1
	v_bfe_u32 v57, v48, 16, 1
	v_bfe_u32 v74, v68, 16, 1
	v_bfe_u32 v75, v69, 16, 1
	v_bfe_u32 v76, v46, 16, 1
	v_bfe_u32 v77, v47, 16, 1
	v_bfe_u32 v70, v45, 16, 1
	v_bfe_u32 v73, v44, 16, 1
	v_add3_u32 v48, v48, v57, s45
	v_add3_u32 v49, v49, v56, s45
	v_add3_u32 v47, v47, v77, s45
	v_add3_u32 v46, v46, v76, s45
	v_add3_u32 v56, v69, v75, s45
; __device__ __forceinline__ unsigned pk2(float lo, float hi) { return f2bf(lo) | (f2bf(hi) << 16); }
; __device__ __forceinline__ void phase_branch_norm(bf16_t* y, const float* ga, const float* gs, const float* gg, const Ctx cx) {
;     ...
;         const float sa = wave_sum(ss[0] + ss[1]), s2 = wave_sum(ss[2]), s3 = wave_sum(ss[3]);
;         const float ra = 1.0f / sqrtf(sa * (1.0f / 1024.f) + EPS), rs = 1.0f / sqrtf(s2 * (1.0f / 512.f) + EPS), rg = 1.0f / sqrtf(s3 * (1.0f / 512.f) + EPS);
; #pragma unroll
;         for (int j = 0; j < 4; ++j) { const float r = (j < 2) ? ra : (j == 2 ? rs : rg);
;             u32x4 w; w.x = pk2(v[j][0] * r * gv[j][0], v[j][1] * r * gv[j][1]); w.y = pk2(v[j][2] * r * gv[j][2], v[j][3] * r * gv[j][3]);
;             w.z = pk2(v[j][4] * r * gv[j][4], v[j][5] * r * gv[j][5]); w.w = pk2(v[j][6] * r * gv[j][6], v[j][7] * r * gv[j][7]);
;             *(u32x4*)(yr + j * 512) = w; }
	v_add3_u32 v57, v68, v74, s45
	v_add3_u32 v44, v44, v73, s45
	v_add3_u32 v45, v45, v70, s45
	v_lshrrev_b32_e32 v57, 16, v57
	v_lshrrev_b32_e32 v56, 16, v56
	v_lshrrev_b32_e32 v46, 16, v46
	v_lshrrev_b32_e32 v47, 16, v47
	v_and_or_b32 v47, v49, s43, v47
	v_and_or_b32 v46, v48, s43, v46
	v_and_or_b32 v45, v45, s43, v56
	v_and_or_b32 v44, v44, s43, v57
	global_store_dwordx4 v[38:39], v[44:47], off
	v_bfe_u32 v48, v43, 16, 1
	v_bfe_u32 v49, v52, 16, 1
	v_bfe_u32 v47, v42, 16, 1
	v_add3_u32 v49, v52, v49, s45
	v_add3_u32 v43, v43, v48, s45
	v_bfe_u32 v78, v55, 16, 1
	v_add3_u32 v42, v42, v47, s45
	v_lshrrev_b32_e32 v47, 16, v49
	v_add3_u32 v46, v55, v78, s45
	v_bfe_u32 v55, v53, 16, 1
	v_add3_u32 v53, v53, v55, s45
	v_bfe_u32 v79, v54, 16, 1
	v_add3_u32 v54, v54, v79, s45
	v_bfe_u32 v80, v51, 16, 1
	s_nop 1
	v_mov_b32_e32 v44, s81
	v_fmamk_f32 v44, v44, 0x3b000000, v194
	v_mul_f32_e32 v45, 0x4f800000, v44
	v_cmp_gt_f32_e32 vcc, s13, v44
	v_bfe_u32 v81, v50, 16, 1
	v_add3_u32 v50, v50, v81, s45
	v_cndmask_b32_e32 v48, v44, v45, vcc
	v_sqrt_f32_e32 v49, v48
	v_lshrrev_b32_e32 v44, 16, v53
	v_and_or_b32 v45, v46, s43, v44
	v_and_or_b32 v44, v54, s43, v47
	v_add_u32_e32 v46, -1, v49
	v_fma_f32 v47, -v46, v49, v48
	v_cmp_ge_f32_e64 s[0:1], 0, v47
	v_add_u32_e32 v47, 1, v49
	v_add3_u32 v51, v51, v80, s45
	v_cndmask_b32_e64 v46, v49, v46, s[0:1]
	v_fma_f32 v49, -v47, v49, v48
	v_cmp_lt_f32_e64 s[0:1], 0, v49
	v_lshrrev_b32_e32 v42, 16, v42
	v_lshrrev_b32_e32 v43, 16, v43
	v_cndmask_b32_e64 v46, v46, v47, s[0:1]
	v_mul_f32_e32 v47, 0x37800000, v46
	v_cndmask_b32_e32 v46, v46, v47, vcc
	v_cmp_class_f32_e32 vcc, v48, v195
	v_and_or_b32 v43, v51, s43, v43
	v_and_or_b32 v42, v50, s43, v42
	v_cndmask_b32_e32 v46, v46, v48, vcc
	v_div_scale_f32 v47, s[0:1], v46, v46, 1.0
	v_rcp_f32_e32 v48, v47
	global_store_dwordx4 v[38:39], v[42:45], off offset:1024
	s_waitcnt vmcnt(2)
	v_lshlrev_b32_e32 v49, 16, v31
	v_and_b32_e32 v51, 0xffff0000, v31
	v_fma_f32 v42, -v47, v48, 1.0
	v_fmac_f32_e32 v48, v42, v48
	v_div_scale_f32 v42, vcc, 1.0, v46, 1.0
	v_mul_f32_e32 v43, v42, v48
	v_fma_f32 v44, -v47, v43, v42
	v_fmac_f32_e32 v43, v44, v48
	v_fma_f32 v42, -v47, v43, v42
	v_div_fmas_f32 v42, v42, v48, v43
	v_lshlrev_b32_e32 v48, 16, v30
	v_and_b32_e32 v50, 0xffff0000, v30
	v_pk_mul_f32 v[30:31], v[48:49], v[48:49]
	v_pk_mul_f32 v[52:53], v[50:51], v[50:51]
	v_lshlrev_b32_e32 v55, 16, v33
	v_add_f32_e32 v30, v30, v52
	v_add_f32_e32 v30, v31, v30
	v_lshlrev_b32_e32 v54, 16, v32
	v_and_b32_e32 v57, 0xffff0000, v33
	v_add_f32_e32 v30, v53, v30
	v_and_b32_e32 v56, 0xffff0000, v32
	v_mov_b32_e32 v32, v57
	v_mov_b32_e32 v33, v55
	v_fmac_f32_e32 v30, v54, v54
	v_pk_mul_f32 v[32:33], v[32:33], v[32:33]
	v_fmac_f32_e32 v30, v56, v56
	v_div_fixup_f32 v42, v42, v46, 1.0
	v_add_f32_e32 v30, v33, v30
	v_pk_mul_f32 v[44:45], v[42:43], v[58:59] op_sel_hi:[0,1]
	v_pk_mul_f32 v[46:47], v[42:43], v[60:61] op_sel_hi:[0,1]
	v_add_f32_e32 v43, v32, v30
	s_nop 1
	v_add_f32_dpp v120, v43, v43 quad_perm:[1,0,3,2] row_mask:0xf bank_mask:0xf
	s_nop 1
	v_add_f32_dpp v120, v120, v120 quad_perm:[2,3,0,1] row_mask:0xf bank_mask:0xf
	s_nop 1
	v_add_f32_dpp v120, v120, v120 row_half_mirror row_mask:0xf bank_mask:0xf
	s_nop 1
	v_add_f32_dpp v120, v120, v120 row_mirror row_mask:0xf bank_mask:0xf
	s_nop 1
	v_add_f32_dpp v120, v120, v120 row_bcast:15 row_mask:0xa bank_mask:0xf
	s_nop 1
	v_add_f32_dpp v120, v120, v120 row_bcast:31 row_mask:0xc bank_mask:0xf
	s_nop 1
	v_readlane_b32 s82, v120, 63
	v_pk_mul_f32 v[32:33], v[42:43], v[34:35] op_sel_hi:[0,1]
	v_pk_mul_f32 v[34:35], v[42:43], v[36:37] op_sel_hi:[0,1]
	v_pk_mul_f32 v[30:31], v[6:7], v[46:47]
	v_pk_mul_f32 v[32:33], v[12:13], v[32:33]
	v_bfe_u32 v46, v31, 16, 1
	v_pk_mul_f32 v[34:35], v[10:11], v[34:35]
	v_bfe_u32 v47, v30, 16, 1
	v_add3_u32 v31, v31, v46, s45
	v_bfe_u32 v46, v32, 16, 1
	v_bfe_u32 v43, v34, 16, 1
	v_add3_u32 v30, v30, v47, s45
	v_bfe_u32 v47, v33, 16, 1
	v_add3_u32 v32, v32, v46, s45
	v_bfe_u32 v42, v35, 16, 1
	v_add3_u32 v34, v34, v43, s45
	v_add3_u32 v33, v33, v47, s45
	v_lshrrev_b32_e32 v32, 16, v32
	v_add3_u32 v35, v35, v42, s45
	v_lshrrev_b32_e32 v33, 16, v33
	v_and_or_b32 v32, v34, s43, v32
	v_and_or_b32 v33, v35, s43, v33
	v_pk_mul_f32 v[44:45], v[8:9], v[44:45]
	s_nop 1
	v_mov_b32_e32 v36, s82
	v_fmamk_f32 v36, v36, 0x3b000000, v194
	v_mul_f32_e32 v37, 0x4f800000, v36
	v_cmp_gt_f32_e32 vcc, s13, v36
	v_bfe_u32 v42, v44, 16, 1
	v_bfe_u32 v43, v45, 16, 1
	v_cndmask_b32_e32 v36, v36, v37, vcc
	v_sqrt_f32_e32 v37, v36
	v_add3_u32 v43, v45, v43, s45
	v_add3_u32 v42, v44, v42, s45
	v_lshrrev_b32_e32 v42, 16, v42
	v_add_u32_e32 v34, -1, v37
	v_fma_f32 v35, -v34, v37, v36
	v_cmp_ge_f32_e64 s[0:1], 0, v35
	v_add_u32_e32 v35, 1, v37
	v_lshrrev_b32_e32 v43, 16, v43
	v_cndmask_b32_e64 v34, v37, v34, s[0:1]
	v_fma_f32 v37, -v35, v37, v36
	v_cmp_lt_f32_e64 s[0:1], 0, v37
	v_and_or_b32 v31, v31, s43, v43
	v_and_or_b32 v30, v30, s43, v42
	v_cndmask_b32_e64 v34, v34, v35, s[0:1]
	v_mul_f32_e32 v35, 0x37800000, v34
	v_cndmask_b32_e32 v34, v34, v35, vcc
	v_cmp_class_f32_e32 vcc, v36, v195
	global_store_dwordx4 v[38:39], v[30:33], off offset:2048
	s_nop 0
	v_cndmask_b32_e32 v34, v34, v36, vcc
	v_div_scale_f32 v35, s[0:1], v34, v34, 1.0
	v_rcp_f32_e32 v36, v35
	s_nop 0
	v_fma_f32 v30, -v35, v36, 1.0
	v_fmac_f32_e32 v36, v30, v36
	v_div_scale_f32 v30, vcc, 1.0, v34, 1.0
	v_mul_f32_e32 v31, v30, v36
	v_fma_f32 v32, -v35, v31, v30
	v_fmac_f32_e32 v31, v32, v36
	v_fma_f32 v30, -v35, v31, v30
	v_div_fmas_f32 v30, v30, v36, v31
	v_div_fixup_f32 v30, v30, v34, 1.0
	v_pk_mul_f32 v[32:33], v[30:31], v[48:49] op_sel_hi:[0,1]
	v_pk_mul_f32 v[34:35], v[30:31], v[50:51] op_sel_hi:[0,1]
	v_pk_mul_f32 v[36:37], v[30:31], v[54:55] op_sel_hi:[0,1]
	v_pk_mul_f32 v[30:31], v[30:31], v[56:57] op_sel_hi:[0,1]
	v_pk_mul_f32 v[34:35], v[40:41], v[34:35]
	v_pk_mul_f32 v[30:31], v[2:3], v[30:31]
	v_pk_mul_f32 v[32:33], v[0:1], v[32:33]
	v_pk_mul_f32 v[36:37], v[4:5], v[36:37]
	v_bfe_u32 v42, v31, 16, 1
	v_bfe_u32 v43, v30, 16, 1
	v_bfe_u32 v44, v35, 16, 1
	v_bfe_u32 v45, v34, 16, 1
	v_add3_u32 v34, v34, v45, s45
	v_add3_u32 v35, v35, v44, s45
	v_add3_u32 v30, v30, v43, s45
	v_add3_u32 v31, v31, v42, s45
	v_bfe_u32 v42, v32, 16, 1
	v_bfe_u32 v43, v33, 16, 1
	v_bfe_u32 v44, v36, 16, 1
	v_bfe_u32 v45, v37, 16, 1
	v_add3_u32 v37, v37, v45, s45
	v_add3_u32 v36, v36, v44, s45
	v_add3_u32 v33, v33, v43, s45
	v_add3_u32 v32, v32, v42, s45
	v_lshrrev_b32_e32 v42, 16, v32
	v_lshrrev_b32_e32 v43, 16, v33
	v_lshrrev_b32_e32 v32, 16, v36
	v_lshrrev_b32_e32 v33, 16, v37
	v_and_or_b32 v33, v31, s43, v33
	v_and_or_b32 v32, v30, s43, v32
	v_and_or_b32 v31, v35, s43, v43
	v_and_or_b32 v30, v34, s43, v42
	global_store_dwordx4 v[38:39], v[30:33], off offset:3072
	v_lshl_add_u64 v[38:39], v[38:39], 0, s[8:9]
	s_cbranch_scc1 .LBB0_467
